# GEMM1 (E2) K-loop first iteration peeled with SrcC=0 too, its two accumulator zeroing blocks removed
# baseline (speedup 1.0000x reference)
; #define PG8_STAGE(bufoff, gbase, voff) do { _Pragma("unroll") for (int _i = 0; _i < 2; ++_i) \
;         __builtin_amdgcn_global_load_lds((const unsigned*)((const char*)(gbase) + (voff)[_i]), (PG8_LAS unsigned*)(lds + (bufoff) + ldsw + _i * 8192), 16, 0, 0); } while (0)
; #define PG8_WAIT_V(n) asm volatile("s_waitcnt vmcnt(" #n ")" ::: "memory")
; #define PG8_BAR __builtin_amdgcn_s_barrier()
; template <class Epi, class Sched>
; __device__ __forceinline__ void gemm_phase(PG8_LAS unsigned char* lds, const Gemm g, const Sched& S, const Epi& E) {
;     int tid = threadIdx.x; asm volatile("" : "+v"(tid));
;     const int wid = __builtin_amdgcn_readfirstlane(tid >> 6), lane = tid & 63, wr = wid >> 2, wc = wid & 3, fr = lane & 15, fq = lane >> 4;
;     const int K = g.K, nt = K / BK;
;     unsigned voffA[2], voffB[2];
; #pragma unroll
;     for (int i = 0; i < 2; ++i) { int R, C; stage_rc(tid * 16 + i * 8192, R, C); const int Rb = Epi::PERM ? ((R & ~31) + perm32(R & 31)) : R;
;         voffA[i] = (unsigned)(R * K + C) * 2u; voffB[i] = (unsigned)(Rb * K + C) * 2u; }
;     const size_t kstep = (size_t)(BK * 2);
;     const size_t hstep = (size_t)HALF * K * 2;
;     const size_t tstep = 2 * hstep;
;     const unsigned ldsw = (unsigned)wid * 1024u;
;     const int aoff = lds_byte(wr * 64 + fr, fq * 8), boff = lds_byte(wc * 32 + fr, fq * 8);
;     ...
;     Unit cur, nxt; int ui = 0;
;     if (!S.next(0, cur)) return;
;     f32x4 acc[2][2][4][2];
; #pragma unroll
;     for (int a = 0; a < 2; ++a)
; #pragma unroll
;         for (int b = 0; b < 2; ++b)
; #pragma unroll
;             for (int m = 0; m < 4; ++m)
; #pragma unroll
;                 for (int n = 0; n < 2; ++n) acc[a][b][m][n] = (f32x4){0.f, 0.f, 0.f, 0.f};
;     bf16x8 At[4][2], B0[2][2], B1[2][2];
;     const char* cA = (const char*)g.A + (size_t)cur.pm * tstep; const char* cB = (const char*)g.Bt + (size_t)cur.pn * tstep;
;     PG8_STAGE(PG8_SB(0, 0), cB, voffB); PG8_STAGE(PG8_SB(0, 1), cB + hstep, voffB); PG8_STAGE(PG8_SA(0, 0), cA, voffA); PG8_STAGE(PG8_SA(0, 1), cA + hstep, voffA);
;     if (wr == 1) PG8_BAR;
;     PG8_WAIT_V(2); PG8_BAR;
;     PG8_STAGE(PG8_SB(1, 0), cB + kstep, voffB); PG8_STAGE(PG8_SA(1, 0), cA + kstep, voffA); PG8_STAGE(PG8_SB(1, 1), cB + hstep + kstep, voffB);
;     PG8_WAIT_V(6); PG8_BAR;
.LBB0_503:
	v_mov_b32_e32 v203, v0
	v_and_b32_e32 v201, 15, v1
	v_lshl_add_u64 v[8:9], s[46:47], 0, v[202:203]
	v_mov_b32_e32 v207, v0
	v_bfe_u32 v199, v1, 4, 2
	v_lshlrev_b32_e32 v20, 6, v201
	v_lshlrev_b32_e32 v1, 2, v1
	v_lshl_add_u64 v[10:11], s[46:47], 0, v[206:207]
	v_mov_b32_e32 v195, v0
	s_and_b32 s33, s2, 3
	v_lshl_or_b32 v20, v199, 4, v20
	s_lshl_b32 s4, s24, 13
	v_and_b32_e32 v1, 32, v1
	s_add_i32 m0, s22, 0x18000
	v_lshl_add_u64 v[8:9], v[8:9], 0, s[0:1]
	v_lshl_add_u64 v[16:17], s[44:45], 0, v[194:195]
	v_mov_b32_e32 v205, v0
	v_bitop3_b32 v21, v20, s4, v1 bitop3:0xde
	s_lshl_b32 s4, s33, 12
	s_waitcnt vmcnt(2)
	s_barrier
	global_load_lds_dwordx4 v[8:9], off
	v_lshl_add_u64 v[8:9], v[10:11], 0, s[0:1]
	s_add_i32 m0, s22, 0x1a000
	s_add_i32 s39, s22, 0x8000
	v_lshl_add_u64 v[18:19], s[44:45], 0, v[204:205]
	v_bitop3_b32 v218, v20, s4, v1 bitop3:0xde
	global_load_lds_dwordx4 v[8:9], off
	v_lshl_add_u64 v[8:9], v[16:17], 0, s[0:1]
	s_mov_b32 m0, s39
	s_add_i32 s4, s22, 0xa000
	v_lshl_add_u64 v[12:13], s[20:21], 0, v[202:203]
	global_load_lds_dwordx4 v[8:9], off
	v_lshl_add_u64 v[8:9], v[18:19], 0, s[0:1]
	s_mov_b32 m0, s4
	v_lshl_add_u64 v[14:15], s[20:21], 0, v[206:207]
	global_load_lds_dwordx4 v[8:9], off
	s_add_i32 m0, s22, 0x1c000
	v_lshl_add_u64 v[8:9], v[12:13], 0, s[0:1]
	global_load_lds_dwordx4 v[8:9], off
	v_lshl_add_u64 v[8:9], v[14:15], 0, s[0:1]
	s_add_i32 m0, s22, 0x1e000
	v_readlane_b32 s15, v255, 15
	global_load_lds_dwordx4 v[8:9], off
	s_mul_i32 s37, s15, s5
	v_cvt_f32_u32_e32 v1, s37
	s_lshr_b32 s2, s18, 6
	s_add_i32 s38, s2, -2
	s_cmpk_lt_u32 s14, 0x100
	v_rcp_iflag_f32_e32 v1, v1
	s_cselect_b64 s[20:21], -1, 0
	s_sub_i32 s14, 0, s37
	s_waitcnt vmcnt(6)
	v_mul_f32_e32 v1, 0x4f7ffffe, v1
	v_cvt_u32_f32_e32 v1, v1
	s_mov_b32 s31, s71
	s_lshr_b32 s99, s30, 3
	s_mov_b32 s76, 0
	v_readfirstlane_b32 s15, v1
	v_add_u32_e32 v1, v4, v2
	v_add_lshl_u32 v2, v1, v3, 1
	v_mov_b32_e32 v3, v0
	v_add_u32_e32 v1, v7, v5
	s_mul_i32 s14, s14, s15
	v_lshl_add_u64 v[208:209], s[70:71], 0, v[2:3]
	v_add_lshl_u32 v2, v1, v6, 1
	s_mul_hi_u32 s14, s15, s14
	v_lshl_add_u64 v[210:211], s[70:71], 0, v[2:3]
	s_add_i32 s72, s15, s14
	v_add_u32_e32 v219, 0, v21
	s_barrier
	s_branch .LBB0_506

; #define PG8_STAGE(bufoff, gbase, voff) do { _Pragma("unroll") for (int _i = 0; _i < 2; ++_i) \
;         __builtin_amdgcn_global_load_lds((const unsigned*)((const char*)(gbase) + (voff)[_i]), (PG8_LAS unsigned*)(lds + (bufoff) + ldsw + _i * 8192), 16, 0, 0); } while (0)
; #define PG8_LDA(dst, b, h) do { _Pragma("unroll") for (int m = 0; m < 4; ++m) _Pragma("unroll") for (int k = 0; k < 2; ++k) dst[m][k] = *(const PG8_LAS bf16x8*)(lds + PG8_SA(b, h) + aoff + m * 2048 + k * 1024); } while (0)
; #define PG8_LDB(dst, b, h) do { _Pragma("unroll") for (int n = 0; n < 2; ++n) _Pragma("unroll") for (int k = 0; k < 2; ++k) dst[n][k] = *(const PG8_LAS bf16x8*)(lds + PG8_SB(b, h) + boff + n * 2048 + k * 1024); } while (0)
; #define PG8_MMA(ai, bj, At, Bt) do { __builtin_amdgcn_s_setprio(1); _Pragma("unroll") for (int m = 0; m < 4; ++m) _Pragma("unroll") for (int n = 0; n < 2; ++n) _Pragma("unroll") for (int k = 0; k < 2; ++k) \
;         acc[ai][bj][m][n] = __builtin_amdgcn_mfma_f32_16x16x32_bf16(Bt[n][k], At[m][k], acc[ai][bj][m][n], 0, 0, 0); __builtin_amdgcn_s_setprio(0); } while (0)
; #define PG8_WAIT_V(n) asm volatile("s_waitcnt vmcnt(" #n ")" ::: "memory")
; #define PG8_WAIT_L(n) asm volatile("s_waitcnt lgkmcnt(" #n ")" ::: "memory")
; #define PG8_BAR __builtin_amdgcn_s_barrier()
; #define PG8_SCHED __builtin_amdgcn_sched_barrier(0)
; template <class Epi, class Sched>
; __device__ __forceinline__ void gemm_phase(PG8_LAS unsigned char* lds, const Gemm g, const Sched& S, const Epi& E) {
;     ...
;         for (int t = 0; t < nt; t += 2) {
;             const bool last = (t == nt - 2);
;             const char* a1 = cA + (size_t)(t + 1) * kstep;
;             const char* a2 = last ? nA : cA + (size_t)(t + 2) * kstep; const char* b2 = last ? nB : cB + (size_t)(t + 2) * kstep;
;             const char* a3 = a2 + kstep; const char* b3 = b2 + kstep;
;             PG8_LDB(B0, 0, 0); PG8_LDB(B1, 0, 1); PG8_SCHED; PG8_LDA(At, 0, 0); PG8_STAGE(PG8_SA(1, 1), a1 + hstep, voffA);
;             PG8_WAIT_V(8); PG8_WAIT_L(0); PG8_BAR; PG8_MMA(0, 0, At, B0); PG8_MMA(0, 1, At, B1); PG8_BAR; PG8_SCHED;
;             PG8_LDA(At, 0, 1); PG8_STAGE(PG8_SB(0, 0), b2, voffB); PG8_STAGE(PG8_SB(0, 1), b2 + hstep, voffB); PG8_STAGE(PG8_SA(0, 0), a2, voffA);
;             PG8_WAIT_V(8); PG8_WAIT_L(0); PG8_BAR; PG8_MMA(1, 0, At, B0); PG8_MMA(1, 1, At, B1); PG8_BAR; PG8_SCHED;
.LBB0_517:
	s_add_u32 s44, s44, 0x80
	s_addc_u32 s45, s45, 0
	s_add_u32 s14, s46, 0x100
	s_addc_u32 s15, s47, 0
	s_mov_b32 s18, 0
	s_waitcnt vmcnt(0)
	s_add_i32 s34, s18, 2
	s_add_u32 s35, s44, 0x80
	s_addc_u32 s46, s45, 0
	s_add_i32 s50, 0, 0x10000
	s_cmp_eq_u32 s38, s18
	s_cselect_b32 s47, s27, s46
	s_cselect_b32 s46, s26, s35
	v_add_u32_e32 v1, s50, v218
	s_cselect_b32 s49, s43, s15
	s_cselect_b32 s48, s42, s14
	s_add_i32 s18, 0, 0x14000
	s_waitcnt lgkmcnt(0)
	ds_read_b128 v[130:133], v1
	ds_read_b128 v[134:137], v1 offset:1024
	ds_read_b128 v[138:141], v1 offset:2048
	ds_read_b128 v[142:145], v1 offset:3072
	v_add_u32_e32 v1, s18, v218
	ds_read_b128 v[146:149], v1
	ds_read_b128 v[150:153], v1 offset:1024
	ds_read_b128 v[154:157], v1 offset:2048
	ds_read_b128 v[158:161], v1 offset:3072
	v_lshl_add_u64 v[212:213], s[44:45], 0, v[208:209]
	s_add_i32 m0, s22, 0xc000
	ds_read_b128 v[162:165], v219
	ds_read_b128 v[166:169], v219 offset:1024
	ds_read_b128 v[170:173], v219 offset:2048
	ds_read_b128 v[174:177], v219 offset:3072
	ds_read_b128 v[178:181], v219 offset:4096
	ds_read_b128 v[182:185], v219 offset:5120
	ds_read_b128 v[186:189], v219 offset:6144
	ds_read_b128 v[190:193], v219 offset:7168
	global_load_lds_dwordx4 v[212:213], off
	v_lshl_add_u64 v[212:213], s[44:45], 0, v[210:211]
	s_add_i32 m0, s22, 0xe000
	s_nop 0
	global_load_lds_dwordx4 v[212:213], off
	s_waitcnt vmcnt(8)
	s_waitcnt lgkmcnt(0)
	s_barrier
	s_setprio 1
	s_waitcnt lgkmcnt(0)
	v_mfma_f32_16x16x32_bf16 v[126:129], v[130:133], v[162:165], 0
	v_mfma_f32_16x16x32_bf16 v[122:125], v[138:141], v[162:165], 0
	v_mfma_f32_16x16x32_bf16 v[118:121], v[130:133], v[170:173], 0
	v_mfma_f32_16x16x32_bf16 v[114:117], v[138:141], v[170:173], 0
	v_mfma_f32_16x16x32_bf16 v[110:113], v[130:133], v[178:181], 0
	v_mfma_f32_16x16x32_bf16 v[106:109], v[138:141], v[178:181], 0
	v_mfma_f32_16x16x32_bf16 v[102:105], v[130:133], v[186:189], 0
	v_mfma_f32_16x16x32_bf16 v[98:101], v[138:141], v[186:189], 0
	v_mfma_f32_16x16x32_bf16 v[126:129], v[134:137], v[166:169], v[126:129]
	v_mfma_f32_16x16x32_bf16 v[122:125], v[142:145], v[166:169], v[122:125]
	v_mfma_f32_16x16x32_bf16 v[118:121], v[134:137], v[174:177], v[118:121]
	v_mfma_f32_16x16x32_bf16 v[114:117], v[142:145], v[174:177], v[114:117]
	v_mfma_f32_16x16x32_bf16 v[110:113], v[134:137], v[182:185], v[110:113]
	v_mfma_f32_16x16x32_bf16 v[106:109], v[142:145], v[182:185], v[106:109]
	v_mfma_f32_16x16x32_bf16 v[102:105], v[134:137], v[190:193], v[102:105]
	v_mfma_f32_16x16x32_bf16 v[98:101], v[142:145], v[190:193], v[98:101]
	s_setprio 0
	s_setprio 1
	v_mfma_f32_16x16x32_bf16 v[94:97], v[146:149], v[162:165], 0
	v_mfma_f32_16x16x32_bf16 v[90:93], v[154:157], v[162:165], 0
	v_mfma_f32_16x16x32_bf16 v[86:89], v[146:149], v[170:173], 0
	v_mfma_f32_16x16x32_bf16 v[82:85], v[154:157], v[170:173], 0
	v_mfma_f32_16x16x32_bf16 v[78:81], v[146:149], v[178:181], 0
	v_mfma_f32_16x16x32_bf16 v[74:77], v[154:157], v[178:181], 0
	v_mfma_f32_16x16x32_bf16 v[70:73], v[146:149], v[186:189], 0
	v_mfma_f32_16x16x32_bf16 v[66:69], v[154:157], v[186:189], 0
	v_mfma_f32_16x16x32_bf16 v[94:97], v[150:153], v[166:169], v[94:97]
	v_mfma_f32_16x16x32_bf16 v[90:93], v[158:161], v[166:169], v[90:93]
	v_mfma_f32_16x16x32_bf16 v[86:89], v[150:153], v[174:177], v[86:89]
	v_mfma_f32_16x16x32_bf16 v[82:85], v[158:161], v[174:177], v[82:85]
	v_mfma_f32_16x16x32_bf16 v[78:81], v[150:153], v[182:185], v[78:81]
	v_mfma_f32_16x16x32_bf16 v[74:77], v[158:161], v[182:185], v[74:77]
	v_mfma_f32_16x16x32_bf16 v[70:73], v[150:153], v[190:193], v[70:73]
	v_mfma_f32_16x16x32_bf16 v[66:69], v[158:161], v[190:193], v[66:69]
	s_setprio 0
	s_barrier
	s_add_i32 s35, s50, s25
	v_lshl_add_u64 v[212:213], s[48:49], 0, v[202:203]
	s_mov_b32 m0, s35
	ds_read_b128 v[162:165], v219 offset:16384
	ds_read_b128 v[166:169], v219 offset:17408
	ds_read_b128 v[170:173], v219 offset:18432
	ds_read_b128 v[174:177], v219 offset:19456
	ds_read_b128 v[178:181], v219 offset:20480
	ds_read_b128 v[182:185], v219 offset:21504
	ds_read_b128 v[186:189], v219 offset:22528
	ds_read_b128 v[190:193], v219 offset:23552
	global_load_lds_dwordx4 v[212:213], off
	s_add_i32 m0, s35, 0x2000
	v_lshl_add_u64 v[214:215], s[48:49], 0, v[206:207]
	s_add_u32 s48, s48, s70
	s_addc_u32 s49, s49, 0
	s_add_i32 s18, s18, s25
	global_load_lds_dwordx4 v[214:215], off
	v_lshl_add_u64 v[216:217], s[48:49], 0, v[202:203]
	s_mov_b32 m0, s18
	v_lshl_add_u64 v[220:221], s[48:49], 0, v[206:207]
	global_load_lds_dwordx4 v[216:217], off
	s_add_i32 m0, s18, 0x2000
	v_lshl_add_u64 v[222:223], s[46:47], 0, v[194:195]
	global_load_lds_dwordx4 v[220:221], off
	s_mov_b32 m0, s22
	v_lshl_add_u64 v[224:225], s[46:47], 0, v[204:205]
	global_load_lds_dwordx4 v[222:223], off
	s_mov_b32 m0, s92
	s_nop 0
	global_load_lds_dwordx4 v[224:225], off
	s_waitcnt vmcnt(8)
	s_waitcnt lgkmcnt(0)
	s_barrier
; #define PG8_STAGE(bufoff, gbase, voff) do { _Pragma("unroll") for (int _i = 0; _i < 2; ++_i) \
;         __builtin_amdgcn_global_load_lds((const unsigned*)((const char*)(gbase) + (voff)[_i]), (PG8_LAS unsigned*)(lds + (bufoff) + ldsw + _i * 8192), 16, 0, 0); } while (0)
; #define PG8_LDA(dst, b, h) do { _Pragma("unroll") for (int m = 0; m < 4; ++m) _Pragma("unroll") for (int k = 0; k < 2; ++k) dst[m][k] = *(const PG8_LAS bf16x8*)(lds + PG8_SA(b, h) + aoff + m * 2048 + k * 1024); } while (0)
; #define PG8_LDB(dst, b, h) do { _Pragma("unroll") for (int n = 0; n < 2; ++n) _Pragma("unroll") for (int k = 0; k < 2; ++k) dst[n][k] = *(const PG8_LAS bf16x8*)(lds + PG8_SB(b, h) + boff + n * 2048 + k * 1024); } while (0)
; #define PG8_MMA(ai, bj, At, Bt) do { __builtin_amdgcn_s_setprio(1); _Pragma("unroll") for (int m = 0; m < 4; ++m) _Pragma("unroll") for (int n = 0; n < 2; ++n) _Pragma("unroll") for (int k = 0; k < 2; ++k) \
;         acc[ai][bj][m][n] = __builtin_amdgcn_mfma_f32_16x16x32_bf16(Bt[n][k], At[m][k], acc[ai][bj][m][n], 0, 0, 0); __builtin_amdgcn_s_setprio(0); } while (0)
; #define PG8_WAIT_V(n) asm volatile("s_waitcnt vmcnt(" #n ")" ::: "memory")
; #define PG8_WAIT_L(n) asm volatile("s_waitcnt lgkmcnt(" #n ")" ::: "memory")
; #define PG8_BAR __builtin_amdgcn_s_barrier()
; #define PG8_SCHED __builtin_amdgcn_sched_barrier(0)
; template <class Epi, class Sched>
; __device__ __forceinline__ void gemm_phase(PG8_LAS unsigned char* lds, const Gemm g, const Sched& S, const Epi& E) {
;     ...
;             PG8_WAIT_V(8); PG8_WAIT_L(0); PG8_BAR; PG8_MMA(1, 0, At, B0); PG8_MMA(1, 1, At, B1); PG8_BAR; PG8_SCHED;
;             PG8_LDB(B0, 1, 0); PG8_LDB(B1, 1, 1); PG8_SCHED; PG8_LDA(At, 1, 0); PG8_STAGE(PG8_SA(0, 1), a2 + hstep, voffA);
;             PG8_WAIT_V(8); PG8_WAIT_L(0); PG8_BAR; PG8_MMA(0, 0, At, B0); PG8_MMA(0, 1, At, B1); PG8_BAR; PG8_SCHED;
;             PG8_LDA(At, 1, 1); PG8_STAGE(PG8_SB(1, 0), b3, voffB); PG8_STAGE(PG8_SB(1, 1), b3 + hstep, voffB); PG8_STAGE(PG8_SA(1, 0), a3, voffA);
;             PG8_WAIT_V(8); PG8_WAIT_L(0); PG8_BAR; PG8_MMA(1, 0, At, B0); PG8_MMA(1, 1, At, B1); PG8_BAR; PG8_SCHED;
	s_setprio 1
	s_waitcnt lgkmcnt(0)
	v_mfma_f32_16x16x32_bf16 v[62:65], v[130:133], v[162:165], 0
	v_mfma_f32_16x16x32_bf16 v[58:61], v[138:141], v[162:165], 0
	v_mfma_f32_16x16x32_bf16 v[54:57], v[130:133], v[170:173], 0
	v_mfma_f32_16x16x32_bf16 v[50:53], v[138:141], v[170:173], 0
	v_mfma_f32_16x16x32_bf16 v[46:49], v[130:133], v[178:181], 0
	v_mfma_f32_16x16x32_bf16 v[42:45], v[138:141], v[178:181], 0
	v_mfma_f32_16x16x32_bf16 v[38:41], v[130:133], v[186:189], 0
	v_mfma_f32_16x16x32_bf16 v[34:37], v[138:141], v[186:189], 0
	v_mfma_f32_16x16x32_bf16 v[62:65], v[134:137], v[166:169], v[62:65]
	v_mfma_f32_16x16x32_bf16 v[58:61], v[142:145], v[166:169], v[58:61]
	v_mfma_f32_16x16x32_bf16 v[54:57], v[134:137], v[174:177], v[54:57]
	v_mfma_f32_16x16x32_bf16 v[50:53], v[142:145], v[174:177], v[50:53]
	v_mfma_f32_16x16x32_bf16 v[46:49], v[134:137], v[182:185], v[46:49]
	v_mfma_f32_16x16x32_bf16 v[42:45], v[142:145], v[182:185], v[42:45]
	v_mfma_f32_16x16x32_bf16 v[38:41], v[134:137], v[190:193], v[38:41]
	v_mfma_f32_16x16x32_bf16 v[34:37], v[142:145], v[190:193], v[34:37]
	s_setprio 0
	s_setprio 1
	v_mfma_f32_16x16x32_bf16 v[30:33], v[146:149], v[162:165], 0
	v_mfma_f32_16x16x32_bf16 v[26:29], v[154:157], v[162:165], 0
	v_mfma_f32_16x16x32_bf16 v[22:25], v[146:149], v[170:173], 0
	v_mfma_f32_16x16x32_bf16 v[18:21], v[154:157], v[170:173], 0
	v_mfma_f32_16x16x32_bf16 v[14:17], v[146:149], v[178:181], 0
	v_mfma_f32_16x16x32_bf16 v[10:13], v[154:157], v[178:181], 0
	v_mfma_f32_16x16x32_bf16 v[6:9], v[146:149], v[186:189], 0
	v_mfma_f32_16x16x32_bf16 v[2:5], v[154:157], v[186:189], 0
	v_mfma_f32_16x16x32_bf16 v[30:33], v[150:153], v[166:169], v[30:33]
	v_mfma_f32_16x16x32_bf16 v[26:29], v[158:161], v[166:169], v[26:29]
	v_mfma_f32_16x16x32_bf16 v[22:25], v[150:153], v[174:177], v[22:25]
	v_mfma_f32_16x16x32_bf16 v[18:21], v[158:161], v[174:177], v[18:21]
	v_mfma_f32_16x16x32_bf16 v[14:17], v[150:153], v[182:185], v[14:17]
	v_mfma_f32_16x16x32_bf16 v[10:13], v[158:161], v[182:185], v[10:13]
	v_mfma_f32_16x16x32_bf16 v[6:9], v[150:153], v[190:193], v[6:9]
	v_mfma_f32_16x16x32_bf16 v[2:5], v[158:161], v[190:193], v[2:5]
	s_setprio 0
	s_barrier
	s_add_i32 s18, 0, 0x18000
	v_add_u32_e32 v1, s18, v218
	s_add_i32 s35, 0, 0x1c000
	ds_read_b128 v[130:133], v1
	ds_read_b128 v[134:137], v1 offset:1024
	ds_read_b128 v[138:141], v1 offset:2048
	ds_read_b128 v[142:145], v1 offset:3072
	v_add_u32_e32 v1, s35, v218
	ds_read_b128 v[146:149], v1
	ds_read_b128 v[150:153], v1 offset:1024
	ds_read_b128 v[154:157], v1 offset:2048
	ds_read_b128 v[158:161], v1 offset:3072
	s_add_u32 s46, s46, s70
	s_addc_u32 s47, s47, 0
	s_mov_b32 m0, s93
	v_lshl_add_u64 v[226:227], s[46:47], 0, v[194:195]
	ds_read_b128 v[162:165], v219 offset:32768
	ds_read_b128 v[166:169], v219 offset:33792
	ds_read_b128 v[170:173], v219 offset:34816
	ds_read_b128 v[174:177], v219 offset:35840
	ds_read_b128 v[178:181], v219 offset:36864
	ds_read_b128 v[182:185], v219 offset:37888
	ds_read_b128 v[186:189], v219 offset:38912
	ds_read_b128 v[190:193], v219 offset:39936
	global_load_lds_dwordx4 v[226:227], off
	v_lshl_add_u64 v[226:227], s[46:47], 0, v[204:205]
	s_mov_b32 m0, s3
	s_nop 0
	global_load_lds_dwordx4 v[226:227], off
	s_waitcnt vmcnt(8)
	s_waitcnt lgkmcnt(0)
	s_barrier
	s_setprio 1
	s_waitcnt lgkmcnt(0)
	v_mfma_f32_16x16x32_bf16 v[126:129], v[130:133], v[162:165], v[126:129]
	v_mfma_f32_16x16x32_bf16 v[122:125], v[138:141], v[162:165], v[122:125]
	v_mfma_f32_16x16x32_bf16 v[118:121], v[130:133], v[170:173], v[118:121]
	v_mfma_f32_16x16x32_bf16 v[114:117], v[138:141], v[170:173], v[114:117]
	v_mfma_f32_16x16x32_bf16 v[110:113], v[130:133], v[178:181], v[110:113]
	v_mfma_f32_16x16x32_bf16 v[106:109], v[138:141], v[178:181], v[106:109]
	v_mfma_f32_16x16x32_bf16 v[102:105], v[130:133], v[186:189], v[102:105]
	v_mfma_f32_16x16x32_bf16 v[98:101], v[138:141], v[186:189], v[98:101]
	v_mfma_f32_16x16x32_bf16 v[126:129], v[134:137], v[166:169], v[126:129]
	v_mfma_f32_16x16x32_bf16 v[122:125], v[142:145], v[166:169], v[122:125]
	v_mfma_f32_16x16x32_bf16 v[118:121], v[134:137], v[174:177], v[118:121]
	v_mfma_f32_16x16x32_bf16 v[114:117], v[142:145], v[174:177], v[114:117]
	v_mfma_f32_16x16x32_bf16 v[110:113], v[134:137], v[182:185], v[110:113]
	v_mfma_f32_16x16x32_bf16 v[106:109], v[142:145], v[182:185], v[106:109]
	v_mfma_f32_16x16x32_bf16 v[102:105], v[134:137], v[190:193], v[102:105]
	v_mfma_f32_16x16x32_bf16 v[98:101], v[142:145], v[190:193], v[98:101]
	s_setprio 0
	s_setprio 1
	v_mfma_f32_16x16x32_bf16 v[94:97], v[146:149], v[162:165], v[94:97]
	v_mfma_f32_16x16x32_bf16 v[90:93], v[154:157], v[162:165], v[90:93]
	v_mfma_f32_16x16x32_bf16 v[86:89], v[146:149], v[170:173], v[86:89]
	v_mfma_f32_16x16x32_bf16 v[82:85], v[154:157], v[170:173], v[82:85]
	v_mfma_f32_16x16x32_bf16 v[78:81], v[146:149], v[178:181], v[78:81]
	v_mfma_f32_16x16x32_bf16 v[74:77], v[154:157], v[178:181], v[74:77]
	v_mfma_f32_16x16x32_bf16 v[70:73], v[146:149], v[186:189], v[70:73]
	v_mfma_f32_16x16x32_bf16 v[66:69], v[154:157], v[186:189], v[66:69]
	v_mfma_f32_16x16x32_bf16 v[94:97], v[150:153], v[166:169], v[94:97]
	v_mfma_f32_16x16x32_bf16 v[90:93], v[158:161], v[166:169], v[90:93]
	v_mfma_f32_16x16x32_bf16 v[86:89], v[150:153], v[174:177], v[86:89]
	v_mfma_f32_16x16x32_bf16 v[82:85], v[158:161], v[174:177], v[82:85]
	v_mfma_f32_16x16x32_bf16 v[78:81], v[150:153], v[182:185], v[78:81]
	v_mfma_f32_16x16x32_bf16 v[74:77], v[158:161], v[182:185], v[74:77]
	v_mfma_f32_16x16x32_bf16 v[70:73], v[150:153], v[190:193], v[70:73]
	v_mfma_f32_16x16x32_bf16 v[66:69], v[158:161], v[190:193], v[66:69]
	s_setprio 0
	s_barrier
; #define PG8_STAGE(bufoff, gbase, voff) do { _Pragma("unroll") for (int _i = 0; _i < 2; ++_i) \
;         __builtin_amdgcn_global_load_lds((const unsigned*)((const char*)(gbase) + (voff)[_i]), (PG8_LAS unsigned*)(lds + (bufoff) + ldsw + _i * 8192), 16, 0, 0); } while (0)
; #define PG8_LDA(dst, b, h) do { _Pragma("unroll") for (int m = 0; m < 4; ++m) _Pragma("unroll") for (int k = 0; k < 2; ++k) dst[m][k] = *(const PG8_LAS bf16x8*)(lds + PG8_SA(b, h) + aoff + m * 2048 + k * 1024); } while (0)
; #define PG8_LDB(dst, b, h) do { _Pragma("unroll") for (int n = 0; n < 2; ++n) _Pragma("unroll") for (int k = 0; k < 2; ++k) dst[n][k] = *(const PG8_LAS bf16x8*)(lds + PG8_SB(b, h) + boff + n * 2048 + k * 1024); } while (0)
; #define PG8_MMA(ai, bj, At, Bt) do { __builtin_amdgcn_s_setprio(1); _Pragma("unroll") for (int m = 0; m < 4; ++m) _Pragma("unroll") for (int n = 0; n < 2; ++n) _Pragma("unroll") for (int k = 0; k < 2; ++k) \
;         acc[ai][bj][m][n] = __builtin_amdgcn_mfma_f32_16x16x32_bf16(Bt[n][k], At[m][k], acc[ai][bj][m][n], 0, 0, 0); __builtin_amdgcn_s_setprio(0); } while (0)
; #define PG8_WAIT_V(n) asm volatile("s_waitcnt vmcnt(" #n ")" ::: "memory")
; #define PG8_WAIT_L(n) asm volatile("s_waitcnt lgkmcnt(" #n ")" ::: "memory")
; #define PG8_BAR __builtin_amdgcn_s_barrier()
; #define PG8_SCHED __builtin_amdgcn_sched_barrier(0)
; template <class Epi, class Sched>
; __device__ __forceinline__ void gemm_phase(PG8_LAS unsigned char* lds, const Gemm g, const Sched& S, const Epi& E) {
;     ...
;             PG8_LDB(B0, 1, 0); PG8_LDB(B1, 1, 1); PG8_SCHED; PG8_LDA(At, 1, 0); PG8_STAGE(PG8_SA(0, 1), a2 + hstep, voffA);
;             PG8_WAIT_V(8); PG8_WAIT_L(0); PG8_BAR; PG8_MMA(0, 0, At, B0); PG8_MMA(0, 1, At, B1); PG8_BAR; PG8_SCHED;
;             PG8_LDA(At, 1, 1); PG8_STAGE(PG8_SB(1, 0), b3, voffB); PG8_STAGE(PG8_SB(1, 1), b3 + hstep, voffB); PG8_STAGE(PG8_SA(1, 0), a3, voffA);
;             PG8_WAIT_V(8); PG8_WAIT_L(0); PG8_BAR; PG8_MMA(1, 0, At, B0); PG8_MMA(1, 1, At, B1); PG8_BAR; PG8_SCHED;
;         }
	s_add_i32 s18, s18, s25
	v_lshl_add_u64 v[212:213], v[212:213], 0, s[0:1]
	s_mov_b32 m0, s18
	ds_read_b128 v[162:165], v219 offset:49152
	ds_read_b128 v[166:169], v219 offset:50176
	ds_read_b128 v[170:173], v219 offset:51200
	ds_read_b128 v[174:177], v219 offset:52224
	ds_read_b128 v[178:181], v219 offset:53248
	ds_read_b128 v[182:185], v219 offset:54272
	ds_read_b128 v[186:189], v219 offset:55296
	ds_read_b128 v[190:193], v219 offset:56320
	global_load_lds_dwordx4 v[212:213], off
	v_lshl_add_u64 v[212:213], v[214:215], 0, s[0:1]
	s_add_i32 m0, s18, 0x2000
	s_add_i32 s18, s35, s25
	global_load_lds_dwordx4 v[212:213], off
	v_lshl_add_u64 v[212:213], v[216:217], 0, s[0:1]
	s_mov_b32 m0, s18
	s_nop 0
	global_load_lds_dwordx4 v[212:213], off
	v_lshl_add_u64 v[212:213], v[220:221], 0, s[0:1]
	s_add_i32 m0, s18, 0x2000
	s_nop 0
	global_load_lds_dwordx4 v[212:213], off
	v_lshl_add_u64 v[212:213], v[222:223], 0, s[0:1]
	s_mov_b32 m0, s39
	s_nop 0
	global_load_lds_dwordx4 v[212:213], off
	v_lshl_add_u64 v[212:213], v[224:225], 0, s[0:1]
	s_mov_b32 m0, s4
	s_nop 0
	global_load_lds_dwordx4 v[212:213], off
	s_waitcnt vmcnt(8)
	s_waitcnt lgkmcnt(0)
	s_barrier
	s_setprio 1
	s_waitcnt lgkmcnt(0)
	v_mfma_f32_16x16x32_bf16 v[62:65], v[130:133], v[162:165], v[62:65]
	v_mfma_f32_16x16x32_bf16 v[58:61], v[138:141], v[162:165], v[58:61]
	v_mfma_f32_16x16x32_bf16 v[54:57], v[130:133], v[170:173], v[54:57]
	v_mfma_f32_16x16x32_bf16 v[50:53], v[138:141], v[170:173], v[50:53]
	v_mfma_f32_16x16x32_bf16 v[46:49], v[130:133], v[178:181], v[46:49]
	v_mfma_f32_16x16x32_bf16 v[42:45], v[138:141], v[178:181], v[42:45]
	v_mfma_f32_16x16x32_bf16 v[38:41], v[130:133], v[186:189], v[38:41]
	v_mfma_f32_16x16x32_bf16 v[34:37], v[138:141], v[186:189], v[34:37]
	v_mfma_f32_16x16x32_bf16 v[62:65], v[134:137], v[166:169], v[62:65]
	v_mfma_f32_16x16x32_bf16 v[58:61], v[142:145], v[166:169], v[58:61]
	v_mfma_f32_16x16x32_bf16 v[54:57], v[134:137], v[174:177], v[54:57]
	v_mfma_f32_16x16x32_bf16 v[50:53], v[142:145], v[174:177], v[50:53]
	v_mfma_f32_16x16x32_bf16 v[46:49], v[134:137], v[182:185], v[46:49]
	v_mfma_f32_16x16x32_bf16 v[42:45], v[142:145], v[182:185], v[42:45]
	v_mfma_f32_16x16x32_bf16 v[38:41], v[134:137], v[190:193], v[38:41]
	v_mfma_f32_16x16x32_bf16 v[34:37], v[142:145], v[190:193], v[34:37]
	s_setprio 0
	s_setprio 1
	v_mfma_f32_16x16x32_bf16 v[30:33], v[146:149], v[162:165], v[30:33]
	v_mfma_f32_16x16x32_bf16 v[26:29], v[154:157], v[162:165], v[26:29]
	v_mfma_f32_16x16x32_bf16 v[22:25], v[146:149], v[170:173], v[22:25]
	v_mfma_f32_16x16x32_bf16 v[18:21], v[154:157], v[170:173], v[18:21]
	v_mfma_f32_16x16x32_bf16 v[14:17], v[146:149], v[178:181], v[14:17]
	v_mfma_f32_16x16x32_bf16 v[10:13], v[154:157], v[178:181], v[10:13]
	v_mfma_f32_16x16x32_bf16 v[6:9], v[146:149], v[186:189], v[6:9]
	v_mfma_f32_16x16x32_bf16 v[2:5], v[154:157], v[186:189], v[2:5]
	v_mfma_f32_16x16x32_bf16 v[30:33], v[150:153], v[166:169], v[30:33]
	v_mfma_f32_16x16x32_bf16 v[26:29], v[158:161], v[166:169], v[26:29]
	v_mfma_f32_16x16x32_bf16 v[22:25], v[150:153], v[174:177], v[22:25]
	v_mfma_f32_16x16x32_bf16 v[18:21], v[158:161], v[174:177], v[18:21]
	v_mfma_f32_16x16x32_bf16 v[14:17], v[150:153], v[182:185], v[14:17]
	v_mfma_f32_16x16x32_bf16 v[10:13], v[158:161], v[182:185], v[10:13]
	v_mfma_f32_16x16x32_bf16 v[6:9], v[150:153], v[190:193], v[6:9]
	v_mfma_f32_16x16x32_bf16 v[2:5], v[158:161], v[190:193], v[2:5]
	s_setprio 0
	s_barrier
	s_add_u32 s44, s44, 0x100
	s_addc_u32 s45, s45, 0
	s_add_u32 s14, s14, 0x100
	s_addc_u32 s15, s15, 0
	s_cmp_ge_u32 s34, s2
	s_mov_b32 s18, s34

; __device__ __forceinline__ unsigned cvt_pk_bf16(float lo, float hi) { unsigned r; asm volatile("v_cvt_pk_bf16_f32 %0, %1, %2" : "=v"(r) : "v"(lo), "v"(hi)); return r; }
;     __device__ __forceinline__ void operator()(f32x4 (&acc)[2][2][4][2], const Unit& u, int wr, int wc, int fr, int fq, PG8_LAS float* sl) const {
;     ...
;         asm volatile("s_waitcnt lgkmcnt(0)" ::: "memory"); __builtin_amdgcn_s_barrier();
; #pragma unroll
;         for (int bj = 0; bj < 2; ++bj) {
;             const int col = col0 + bj * HALF;
;             const f32x4 g0 = *(const f32x4*)(gam + col), g1 = *(const f32x4*)(gam + col + 4), b0 = *(const f32x4*)(bet + col), b1 = *(const f32x4*)(bet + col + 4);
; #pragma unroll
;             for (int ai = 0; ai < 2; ++ai)
; #pragma unroll
;                 for (int m = 0; m < 4; ++m) {
;                     const int lr = lr0 + ai * HALF + m * 16; const float mu = sl[2 * lr], rstd = sl[2 * lr + 1];
;                     const size_t off = (size_t)(u.pm * BM + lr) * 1024 + col;
;                     const f32x4 y0 = (acc[ai][bj][m][0] - mu) * rstd * g0 + b0, y1 = (acc[ai][bj][m][1] - mu) * rstd * g1 + b1;
;                     *(f32x4*)(Xout + off) = y0; *(f32x4*)(Xout + off + 4) = y1;
;                     u32x4 w; w.x = cvt_pk_bf16(y0[0], y0[1]); w.y = cvt_pk_bf16(y0[2], y0[3]); w.z = cvt_pk_bf16(y1[0], y1[1]); w.w = cvt_pk_bf16(y1[2], y1[3]);
;                     *(u32x4*)(XB + off) = w;
;                     __builtin_amdgcn_sched_barrier(0);
;                 }
;         }
.LBB0_554:
	s_or_b64 exec, exec, s[56:57]
	v_lshlrev_b64 v[130:131], 2, v[212:213]
	v_lshl_add_u64 v[150:151], s[48:49], 0, v[130:131]
	s_waitcnt lgkmcnt(0)
	s_barrier
	v_lshl_add_u64 v[148:149], s[50:51], 0, v[130:131]
	flat_load_dwordx4 v[138:141], v[150:151]
	flat_load_dwordx4 v[142:145], v[148:149]
	s_waitcnt lgkmcnt(0)
	flat_load_dwordx4 v[130:133], v[148:149] offset:16
	flat_load_dwordx4 v[134:137], v[150:151] offset:16
	s_add_i32 s14, 0, 0x20040
	v_add_u32_e32 v182, s14, v221
	ds_read_b64 v[152:153], v182
	v_lshlrev_b64 v[146:147], 10, v[214:215]
	v_lshl_add_u64 v[164:165], v[146:147], 0, v[212:213]
	v_lshl_add_u64 v[146:147], v[164:165], 2, s[46:47]
	v_lshl_add_u32 v1, v192, 3, s14
	s_waitcnt lgkmcnt(0)
	v_sub_f32_e32 v155, v129, v152
	v_sub_f32_e32 v154, v128, v152
	v_sub_f32_e32 v157, v127, v152
	v_sub_f32_e32 v156, v126, v152
	v_sub_f32_e32 v159, v125, v152
	v_sub_f32_e32 v158, v124, v152
	v_sub_f32_e32 v161, v123, v152
	v_sub_f32_e32 v160, v122, v152
	v_pk_mul_f32 v[156:157], v[152:153], v[156:157] op_sel:[1,0]
	v_pk_mul_f32 v[154:155], v[152:153], v[154:155] op_sel:[1,0]
	v_pk_mul_f32 v[160:161], v[152:153], v[160:161] op_sel:[1,0]
	v_pk_mul_f32 v[158:159], v[152:153], v[158:159] op_sel:[1,0]
	s_waitcnt vmcnt(0)
	v_pk_fma_f32 v[154:155], v[144:145], v[154:155], v[140:141]
	v_pk_fma_f32 v[152:153], v[142:143], v[156:157], v[138:139]
	v_pk_fma_f32 v[158:159], v[132:133], v[158:159], v[136:137]
	v_pk_fma_f32 v[156:157], v[130:131], v[160:161], v[134:135]
	flat_store_dwordx4 v[146:147], v[152:155]
	flat_store_dwordx4 v[146:147], v[156:159] offset:16
	v_cvt_pk_bf16_f32 v160, v152, v153
	v_cvt_pk_bf16_f32 v161, v154, v155
	v_cvt_pk_bf16_f32 v162, v156, v157
	v_cvt_pk_bf16_f32 v163, v158, v159
	s_nop 0
	v_lshl_add_u64 v[154:155], v[164:165], 1, s[44:45]
	flat_store_dwordx4 v[154:155], v[160:163]
	v_add_u32_e32 v156, 16, v220
	v_lshl_add_u32 v183, v156, 3, s14
	ds_read_b64 v[152:153], v183
	v_add_u32_e32 v156, s77, v156
	v_ashrrev_i32_e32 v157, 31, v156
	v_lshlrev_b64 v[156:157], 10, v[156:157]
	v_lshl_add_u64 v[168:169], v[156:157], 0, v[212:213]
	s_waitcnt lgkmcnt(0)
	v_sub_f32_e32 v157, v121, v152
	v_sub_f32_e32 v156, v120, v152
	v_sub_f32_e32 v159, v119, v152
	v_sub_f32_e32 v158, v118, v152
	v_pk_mul_f32 v[160:161], v[152:153], v[158:159] op_sel:[1,0]
	v_pk_mul_f32 v[156:157], v[152:153], v[156:157] op_sel:[1,0]
	v_sub_f32_e32 v163, v115, v152
	v_pk_fma_f32 v[158:159], v[144:145], v[156:157], v[140:141]
	v_pk_fma_f32 v[156:157], v[142:143], v[160:161], v[138:139]
	v_sub_f32_e32 v161, v117, v152
	v_sub_f32_e32 v160, v116, v152
	v_sub_f32_e32 v162, v114, v152
	v_pk_mul_f32 v[164:165], v[152:153], v[162:163] op_sel:[1,0]
	v_pk_mul_f32 v[152:153], v[152:153], v[160:161] op_sel:[1,0]
	v_pk_fma_f32 v[160:161], v[130:131], v[164:165], v[134:135]
	v_pk_fma_f32 v[162:163], v[132:133], v[152:153], v[136:137]
	v_lshl_add_u64 v[152:153], v[168:169], 2, s[46:47]
	flat_store_dwordx4 v[152:153], v[156:159]
	flat_store_dwordx4 v[152:153], v[160:163] offset:16
	v_cvt_pk_bf16_f32 v164, v156, v157
	v_cvt_pk_bf16_f32 v165, v158, v159
	v_cvt_pk_bf16_f32 v166, v160, v161
	v_cvt_pk_bf16_f32 v167, v162, v163
	s_nop 0
	v_lshl_add_u64 v[158:159], v[168:169], 1, s[44:45]
	flat_store_dwordx4 v[158:159], v[164:167]
	v_add_u32_e32 v160, 32, v220
	v_lshl_add_u32 v192, v160, 3, s14
	ds_read_b64 v[156:157], v192
	v_add_u32_e32 v160, s77, v160
	v_ashrrev_i32_e32 v161, 31, v160
	v_lshlrev_b64 v[160:161], 10, v[160:161]
	v_lshl_add_u64 v[168:169], v[160:161], 0, v[212:213]
	s_waitcnt lgkmcnt(0)
	v_sub_f32_e32 v161, v113, v156
	v_sub_f32_e32 v160, v112, v156
	v_sub_f32_e32 v163, v111, v156
	v_sub_f32_e32 v162, v110, v156
	v_pk_mul_f32 v[164:165], v[156:157], v[162:163] op_sel:[1,0]
	v_pk_mul_f32 v[160:161], v[156:157], v[160:161] op_sel:[1,0]
	v_sub_f32_e32 v167, v107, v156
	v_pk_fma_f32 v[162:163], v[144:145], v[160:161], v[140:141]
	v_pk_fma_f32 v[160:161], v[142:143], v[164:165], v[138:139]
	v_sub_f32_e32 v165, v109, v156
	v_sub_f32_e32 v164, v108, v156
	v_sub_f32_e32 v166, v106, v156
	v_pk_mul_f32 v[170:171], v[156:157], v[166:167] op_sel:[1,0]
	v_pk_mul_f32 v[156:157], v[156:157], v[164:165] op_sel:[1,0]
	v_pk_fma_f32 v[164:165], v[130:131], v[170:171], v[134:135]
	v_pk_fma_f32 v[166:167], v[132:133], v[156:157], v[136:137]
	v_lshl_add_u64 v[156:157], v[168:169], 2, s[46:47]
	flat_store_dwordx4 v[156:157], v[160:163]
	flat_store_dwordx4 v[156:157], v[164:167] offset:16
	s_nop 0
	v_cvt_pk_bf16_f32 v160, v160, v161
	v_cvt_pk_bf16_f32 v161, v162, v163
	v_cvt_pk_bf16_f32 v162, v164, v165
	v_cvt_pk_bf16_f32 v163, v166, v167
	s_nop 0
	v_lshl_add_u64 v[164:165], v[168:169], 1, s[44:45]
	flat_store_dwordx4 v[164:165], v[160:163]
	s_nop 1
	v_add_u32_e32 v162, 48, v220
	v_lshl_add_u32 v193, v162, 3, s14
	ds_read_b64 v[160:161], v193
	v_add_u32_e32 v162, s77, v162
	v_ashrrev_i32_e32 v163, 31, v162
	v_lshlrev_b64 v[162:163], 10, v[162:163]
	v_lshl_add_u64 v[162:163], v[162:163], 0, v[212:213]
	s_waitcnt lgkmcnt(0)
	v_sub_f32_e32 v167, v105, v160
	v_sub_f32_e32 v166, v104, v160
	v_sub_f32_e32 v169, v103, v160
	v_sub_f32_e32 v168, v102, v160
	v_pk_mul_f32 v[170:171], v[160:161], v[168:169] op_sel:[1,0]
	v_pk_mul_f32 v[166:167], v[160:161], v[166:167] op_sel:[1,0]
	v_sub_f32_e32 v173, v99, v160
	v_pk_fma_f32 v[168:169], v[144:145], v[166:167], v[140:141]
	v_pk_fma_f32 v[166:167], v[142:143], v[170:171], v[138:139]
	v_sub_f32_e32 v171, v101, v160
	v_sub_f32_e32 v170, v100, v160
	v_sub_f32_e32 v172, v98, v160
	v_pk_mul_f32 v[174:175], v[160:161], v[172:173] op_sel:[1,0]
	v_pk_mul_f32 v[160:161], v[160:161], v[170:171] op_sel:[1,0]
	v_pk_fma_f32 v[170:171], v[130:131], v[174:175], v[134:135]
	v_pk_fma_f32 v[172:173], v[132:133], v[160:161], v[136:137]
	v_lshl_add_u64 v[160:161], v[162:163], 2, s[46:47]
	flat_store_dwordx4 v[160:161], v[166:169]
	flat_store_dwordx4 v[160:161], v[170:173] offset:16
	v_cvt_pk_bf16_f32 v174, v166, v167
	v_cvt_pk_bf16_f32 v175, v168, v169
	v_cvt_pk_bf16_f32 v176, v170, v171
	v_cvt_pk_bf16_f32 v177, v172, v173
	s_nop 0
	v_lshl_add_u64 v[168:169], v[162:163], 1, s[44:45]
	flat_store_dwordx4 v[168:169], v[174:177]
	ds_read_b64 v[162:163], v1
	v_lshlrev_b64 v[166:167], 10, v[186:187]
	v_lshl_add_u64 v[166:167], v[166:167], 0, v[212:213]
	s_waitcnt lgkmcnt(0)
; __device__ __forceinline__ unsigned cvt_pk_bf16(float lo, float hi) { unsigned r; asm volatile("v_cvt_pk_bf16_f32 %0, %1, %2" : "=v"(r) : "v"(lo), "v"(hi)); return r; }
;     __device__ __forceinline__ void operator()(f32x4 (&acc)[2][2][4][2], const Unit& u, int wr, int wc, int fr, int fq, PG8_LAS float* sl) const {
;     ...
; #pragma unroll
;         for (int bj = 0; bj < 2; ++bj) {
;             const int col = col0 + bj * HALF;
;             const f32x4 g0 = *(const f32x4*)(gam + col), g1 = *(const f32x4*)(gam + col + 4), b0 = *(const f32x4*)(bet + col), b1 = *(const f32x4*)(bet + col + 4);
; #pragma unroll
;             for (int ai = 0; ai < 2; ++ai)
; #pragma unroll
;                 for (int m = 0; m < 4; ++m) {
;                     const int lr = lr0 + ai * HALF + m * 16; const float mu = sl[2 * lr], rstd = sl[2 * lr + 1];
;                     const size_t off = (size_t)(u.pm * BM + lr) * 1024 + col;
;                     const f32x4 y0 = (acc[ai][bj][m][0] - mu) * rstd * g0 + b0, y1 = (acc[ai][bj][m][1] - mu) * rstd * g1 + b1;
;                     *(f32x4*)(Xout + off) = y0; *(f32x4*)(Xout + off + 4) = y1;
;                     u32x4 w; w.x = cvt_pk_bf16(y0[0], y0[1]); w.y = cvt_pk_bf16(y0[2], y0[3]); w.z = cvt_pk_bf16(y1[0], y1[1]); w.w = cvt_pk_bf16(y1[2], y1[3]);
;                     *(u32x4*)(XB + off) = w;
;                     __builtin_amdgcn_sched_barrier(0);
;                 }
;         }
	v_sub_f32_e32 v171, v65, v162
	v_sub_f32_e32 v170, v64, v162
	v_sub_f32_e32 v173, v63, v162
	v_sub_f32_e32 v172, v62, v162
	v_pk_mul_f32 v[174:175], v[162:163], v[172:173] op_sel:[1,0]
	v_pk_mul_f32 v[170:171], v[162:163], v[170:171] op_sel:[1,0]
	v_sub_f32_e32 v177, v59, v162
	v_pk_fma_f32 v[172:173], v[144:145], v[170:171], v[140:141]
	v_pk_fma_f32 v[170:171], v[142:143], v[174:175], v[138:139]
	v_sub_f32_e32 v175, v61, v162
	v_sub_f32_e32 v174, v60, v162
	v_sub_f32_e32 v176, v58, v162
	v_pk_mul_f32 v[178:179], v[162:163], v[176:177] op_sel:[1,0]
	v_pk_mul_f32 v[162:163], v[162:163], v[174:175] op_sel:[1,0]
	v_pk_fma_f32 v[174:175], v[130:131], v[178:179], v[134:135]
	v_pk_fma_f32 v[176:177], v[132:133], v[162:163], v[136:137]
	v_lshl_add_u64 v[162:163], v[166:167], 2, s[46:47]
	flat_store_dwordx4 v[162:163], v[170:173]
	flat_store_dwordx4 v[162:163], v[174:177] offset:16
	v_cvt_pk_bf16_f32 v178, v170, v171
	v_cvt_pk_bf16_f32 v179, v172, v173
	v_cvt_pk_bf16_f32 v180, v174, v175
	v_cvt_pk_bf16_f32 v181, v176, v177
	s_nop 0
	v_lshl_add_u64 v[170:171], v[166:167], 1, s[44:45]
	flat_store_dwordx4 v[170:171], v[178:181]
	v_add_u32_e32 v172, 0x90, v220
	v_lshl_add_u32 v196, v172, 3, s14
	ds_read_b64 v[166:167], v196
	v_add_u32_e32 v172, s77, v172
	v_ashrrev_i32_e32 v173, 31, v172
	v_lshlrev_b64 v[172:173], 10, v[172:173]
	v_lshl_add_u64 v[180:181], v[172:173], 0, v[212:213]
	s_waitcnt lgkmcnt(0)
	v_sub_f32_e32 v173, v57, v166
	v_sub_f32_e32 v172, v56, v166
	v_sub_f32_e32 v175, v55, v166
	v_sub_f32_e32 v174, v54, v166
	v_pk_mul_f32 v[176:177], v[166:167], v[174:175] op_sel:[1,0]
	v_pk_mul_f32 v[172:173], v[166:167], v[172:173] op_sel:[1,0]
	v_sub_f32_e32 v179, v51, v166
	v_pk_fma_f32 v[174:175], v[144:145], v[172:173], v[140:141]
	v_pk_fma_f32 v[172:173], v[142:143], v[176:177], v[138:139]
	v_sub_f32_e32 v177, v53, v166
	v_sub_f32_e32 v176, v52, v166
	v_sub_f32_e32 v178, v50, v166
	v_pk_mul_f32 v[184:185], v[166:167], v[178:179] op_sel:[1,0]
	v_pk_mul_f32 v[166:167], v[166:167], v[176:177] op_sel:[1,0]
	v_pk_fma_f32 v[176:177], v[130:131], v[184:185], v[134:135]
	v_pk_fma_f32 v[178:179], v[132:133], v[166:167], v[136:137]
	v_lshl_add_u64 v[166:167], v[180:181], 2, s[46:47]
	flat_store_dwordx4 v[166:167], v[172:175]
	flat_store_dwordx4 v[166:167], v[176:179] offset:16
	v_cvt_pk_bf16_f32 v184, v172, v173
	v_cvt_pk_bf16_f32 v185, v174, v175
	v_cvt_pk_bf16_f32 v186, v176, v177
	v_cvt_pk_bf16_f32 v187, v178, v179
	s_nop 0
	v_lshl_add_u64 v[174:175], v[180:181], 1, s[44:45]
	flat_store_dwordx4 v[174:175], v[184:187]
	v_add_u32_e32 v176, 0xa0, v220
	v_lshl_add_u32 v197, v176, 3, s14
	ds_read_b64 v[172:173], v197
	v_add_u32_e32 v176, s77, v176
	v_ashrrev_i32_e32 v177, 31, v176
	v_lshlrev_b64 v[176:177], 10, v[176:177]
	v_lshl_add_u64 v[180:181], v[176:177], 0, v[212:213]
	s_waitcnt lgkmcnt(0)
	v_sub_f32_e32 v177, v49, v172
	v_sub_f32_e32 v176, v48, v172
	v_sub_f32_e32 v179, v47, v172
	v_sub_f32_e32 v178, v46, v172
	v_pk_mul_f32 v[184:185], v[172:173], v[178:179] op_sel:[1,0]
	v_pk_mul_f32 v[176:177], v[172:173], v[176:177] op_sel:[1,0]
	v_sub_f32_e32 v187, v43, v172
	v_pk_fma_f32 v[178:179], v[144:145], v[176:177], v[140:141]
	v_pk_fma_f32 v[176:177], v[142:143], v[184:185], v[138:139]
	v_sub_f32_e32 v185, v45, v172
	v_sub_f32_e32 v184, v44, v172
	v_sub_f32_e32 v186, v42, v172
	v_pk_mul_f32 v[188:189], v[172:173], v[186:187] op_sel:[1,0]
	v_pk_mul_f32 v[172:173], v[172:173], v[184:185] op_sel:[1,0]
	v_pk_fma_f32 v[184:185], v[130:131], v[188:189], v[134:135]
	v_pk_fma_f32 v[186:187], v[132:133], v[172:173], v[136:137]
	v_lshl_add_u64 v[172:173], v[180:181], 2, s[46:47]
	flat_store_dwordx4 v[172:173], v[176:179]
	flat_store_dwordx4 v[172:173], v[184:187] offset:16
	v_cvt_pk_bf16_f32 v188, v176, v177
	v_cvt_pk_bf16_f32 v189, v178, v179
	v_cvt_pk_bf16_f32 v190, v184, v185
	v_cvt_pk_bf16_f32 v191, v186, v187
	s_nop 0
	v_lshl_add_u64 v[178:179], v[180:181], 1, s[44:45]
	flat_store_dwordx4 v[178:179], v[188:191]
	v_add_u32_e32 v180, 0xb0, v220
	s_nop 0
	v_lshl_add_u32 v190, v180, 3, s14
	ds_read_b64 v[176:177], v190
	v_add_u32_e32 v180, s77, v180
	v_ashrrev_i32_e32 v181, 31, v180
	v_lshlrev_b64 v[180:181], 10, v[180:181]
	v_lshl_add_u64 v[180:181], v[180:181], 0, v[212:213]
	s_waitcnt lgkmcnt(0)
	v_sub_f32_e32 v185, v41, v176
	v_sub_f32_e32 v184, v40, v176
	v_sub_f32_e32 v187, v39, v176
	v_sub_f32_e32 v186, v38, v176
	v_pk_mul_f32 v[186:187], v[176:177], v[186:187] op_sel:[1,0]
	v_pk_mul_f32 v[184:185], v[176:177], v[184:185] op_sel:[1,0]
	v_pk_fma_f32 v[138:139], v[142:143], v[186:187], v[138:139]
	v_pk_fma_f32 v[140:141], v[144:145], v[184:185], v[140:141]
	v_sub_f32_e32 v143, v37, v176
	v_sub_f32_e32 v142, v36, v176
	v_sub_f32_e32 v145, v35, v176
	v_sub_f32_e32 v144, v34, v176
	v_pk_mul_f32 v[144:145], v[176:177], v[144:145] op_sel:[1,0]
	v_pk_mul_f32 v[142:143], v[176:177], v[142:143] op_sel:[1,0]
	v_lshl_add_u64 v[176:177], v[180:181], 2, s[46:47]
	v_lshl_add_u64 v[180:181], v[180:181], 1, s[44:45]
	v_pk_fma_f32 v[132:133], v[132:133], v[142:143], v[136:137]
	v_pk_fma_f32 v[130:131], v[130:131], v[144:145], v[134:135]
	flat_store_dwordx4 v[176:177], v[138:141]
	flat_store_dwordx4 v[176:177], v[130:133] offset:16
	v_cvt_pk_bf16_f32 v134, v138, v139
	v_cvt_pk_bf16_f32 v135, v140, v141
	v_cvt_pk_bf16_f32 v136, v130, v131
	v_cvt_pk_bf16_f32 v137, v132, v133
	flat_store_dwordx4 v[180:181], v[134:137]
	flat_load_dwordx4 v[138:141], v[150:151] offset:512
	flat_load_dwordx4 v[142:145], v[148:149] offset:512
	flat_load_dwordx4 v[130:133], v[148:149] offset:528
	s_nop 0
	flat_load_dwordx4 v[134:137], v[150:151] offset:528
	ds_read_b64 v[148:149], v182
	s_waitcnt lgkmcnt(0)
; __device__ __forceinline__ unsigned cvt_pk_bf16(float lo, float hi) { unsigned r; asm volatile("v_cvt_pk_bf16_f32 %0, %1, %2" : "=v"(r) : "v"(lo), "v"(hi)); return r; }
;     __device__ __forceinline__ void operator()(f32x4 (&acc)[2][2][4][2], const Unit& u, int wr, int wc, int fr, int fq, PG8_LAS float* sl) const {
;     ...
;         for (int bj = 0; bj < 2; ++bj) {
;             const int col = col0 + bj * HALF;
;             const f32x4 g0 = *(const f32x4*)(gam + col), g1 = *(const f32x4*)(gam + col + 4), b0 = *(const f32x4*)(bet + col), b1 = *(const f32x4*)(bet + col + 4);
; #pragma unroll
;             for (int ai = 0; ai < 2; ++ai)
; #pragma unroll
;                 for (int m = 0; m < 4; ++m) {
;                     const int lr = lr0 + ai * HALF + m * 16; const float mu = sl[2 * lr], rstd = sl[2 * lr + 1];
;                     const size_t off = (size_t)(u.pm * BM + lr) * 1024 + col;
;                     const f32x4 y0 = (acc[ai][bj][m][0] - mu) * rstd * g0 + b0, y1 = (acc[ai][bj][m][1] - mu) * rstd * g1 + b1;
;                     *(f32x4*)(Xout + off) = y0; *(f32x4*)(Xout + off + 4) = y1;
;                     u32x4 w; w.x = cvt_pk_bf16(y0[0], y0[1]); w.y = cvt_pk_bf16(y0[2], y0[3]); w.z = cvt_pk_bf16(y1[0], y1[1]); w.w = cvt_pk_bf16(y1[2], y1[3]);
;                     *(u32x4*)(XB + off) = w;
;                     __builtin_amdgcn_sched_barrier(0);
;                 }
	v_sub_f32_e32 v151, v97, v148
	v_sub_f32_e32 v150, v96, v148
	v_sub_f32_e32 v185, v95, v148
	v_sub_f32_e32 v184, v94, v148
	v_sub_f32_e32 v187, v93, v148
	v_sub_f32_e32 v186, v92, v148
	v_sub_f32_e32 v189, v91, v148
	v_sub_f32_e32 v188, v90, v148
	v_pk_mul_f32 v[184:185], v[148:149], v[184:185] op_sel:[1,0]
	v_pk_mul_f32 v[150:151], v[148:149], v[150:151] op_sel:[1,0]
	v_pk_mul_f32 v[188:189], v[148:149], v[188:189] op_sel:[1,0]
	v_pk_mul_f32 v[186:187], v[148:149], v[186:187] op_sel:[1,0]
	s_waitcnt vmcnt(0)
	v_pk_fma_f32 v[150:151], v[144:145], v[150:151], v[140:141]
	v_pk_fma_f32 v[148:149], v[142:143], v[184:185], v[138:139]
	v_pk_fma_f32 v[186:187], v[132:133], v[186:187], v[136:137]
	v_pk_fma_f32 v[184:185], v[130:131], v[188:189], v[134:135]
	flat_store_dwordx4 v[146:147], v[148:151] offset:512
	flat_store_dwordx4 v[146:147], v[184:187] offset:528
	v_cvt_pk_bf16_f32 v146, v148, v149
	v_cvt_pk_bf16_f32 v147, v150, v151
	s_nop 0
	v_cvt_pk_bf16_f32 v148, v184, v185
	v_cvt_pk_bf16_f32 v149, v186, v187
	flat_store_dwordx4 v[154:155], v[146:149] offset:256
	ds_read_b64 v[150:151], v183
	s_waitcnt lgkmcnt(0)
	v_sub_f32_e32 v147, v89, v150
	v_sub_f32_e32 v146, v88, v150
	v_sub_f32_e32 v149, v87, v150
	v_sub_f32_e32 v148, v86, v150
	v_pk_mul_f32 v[154:155], v[150:151], v[148:149] op_sel:[1,0]
	v_pk_mul_f32 v[146:147], v[150:151], v[146:147] op_sel:[1,0]
	v_sub_f32_e32 v183, v83, v150
	v_pk_fma_f32 v[148:149], v[144:145], v[146:147], v[140:141]
	v_pk_fma_f32 v[146:147], v[142:143], v[154:155], v[138:139]
	v_sub_f32_e32 v155, v85, v150
	v_sub_f32_e32 v154, v84, v150
	v_sub_f32_e32 v182, v82, v150
	v_pk_mul_f32 v[182:183], v[150:151], v[182:183] op_sel:[1,0]
	v_pk_mul_f32 v[150:151], v[150:151], v[154:155] op_sel:[1,0]
	v_pk_fma_f32 v[182:183], v[130:131], v[182:183], v[134:135]
	v_pk_fma_f32 v[184:185], v[132:133], v[150:151], v[136:137]
	flat_store_dwordx4 v[152:153], v[146:149] offset:512
	flat_store_dwordx4 v[152:153], v[182:185] offset:528
	s_nop 0
	v_cvt_pk_bf16_f32 v146, v146, v147
	v_cvt_pk_bf16_f32 v147, v148, v149
	v_cvt_pk_bf16_f32 v148, v182, v183
	v_cvt_pk_bf16_f32 v149, v184, v185
	flat_store_dwordx4 v[158:159], v[146:149] offset:256
	ds_read_b64 v[150:151], v192
	s_waitcnt lgkmcnt(0)
	v_sub_f32_e32 v147, v81, v150
	v_sub_f32_e32 v146, v80, v150
	v_sub_f32_e32 v149, v79, v150
	v_sub_f32_e32 v148, v78, v150
	v_pk_mul_f32 v[152:153], v[150:151], v[148:149] op_sel:[1,0]
	v_pk_mul_f32 v[146:147], v[150:151], v[146:147] op_sel:[1,0]
	v_sub_f32_e32 v155, v75, v150
	v_pk_fma_f32 v[148:149], v[144:145], v[146:147], v[140:141]
	v_pk_fma_f32 v[146:147], v[142:143], v[152:153], v[138:139]
	v_sub_f32_e32 v153, v77, v150
	v_sub_f32_e32 v152, v76, v150
	v_sub_f32_e32 v154, v74, v150
	v_pk_mul_f32 v[154:155], v[150:151], v[154:155] op_sel:[1,0]
	v_pk_mul_f32 v[150:151], v[150:151], v[152:153] op_sel:[1,0]
	s_nop 0
	v_pk_fma_f32 v[152:153], v[132:133], v[150:151], v[136:137]
	v_pk_fma_f32 v[150:151], v[130:131], v[154:155], v[134:135]
	flat_store_dwordx4 v[156:157], v[146:149] offset:512
	flat_store_dwordx4 v[156:157], v[150:153] offset:528
	s_nop 0
	v_cvt_pk_bf16_f32 v146, v146, v147
	v_cvt_pk_bf16_f32 v147, v148, v149
	v_cvt_pk_bf16_f32 v148, v150, v151
	v_cvt_pk_bf16_f32 v149, v152, v153
	flat_store_dwordx4 v[164:165], v[146:149] offset:256
	ds_read_b64 v[150:151], v193
	s_waitcnt lgkmcnt(0)
	v_sub_f32_e32 v147, v73, v150
	v_sub_f32_e32 v146, v72, v150
	v_sub_f32_e32 v149, v71, v150
	v_sub_f32_e32 v148, v70, v150
	v_pk_mul_f32 v[152:153], v[150:151], v[148:149] op_sel:[1,0]
	v_pk_mul_f32 v[146:147], v[150:151], v[146:147] op_sel:[1,0]
	v_sub_f32_e32 v155, v67, v150
	v_pk_fma_f32 v[148:149], v[144:145], v[146:147], v[140:141]
	v_pk_fma_f32 v[146:147], v[142:143], v[152:153], v[138:139]
	v_sub_f32_e32 v153, v69, v150
	v_sub_f32_e32 v152, v68, v150
	v_sub_f32_e32 v154, v66, v150
	v_pk_mul_f32 v[154:155], v[150:151], v[154:155] op_sel:[1,0]
	v_pk_mul_f32 v[150:151], v[150:151], v[152:153] op_sel:[1,0]
	s_nop 0
	v_pk_fma_f32 v[152:153], v[132:133], v[150:151], v[136:137]
	v_pk_fma_f32 v[150:151], v[130:131], v[154:155], v[134:135]
	flat_store_dwordx4 v[160:161], v[146:149] offset:512
	flat_store_dwordx4 v[160:161], v[150:153] offset:528
	s_nop 0
	v_cvt_pk_bf16_f32 v146, v146, v147
	v_cvt_pk_bf16_f32 v147, v148, v149
	v_cvt_pk_bf16_f32 v148, v150, v151
	v_cvt_pk_bf16_f32 v149, v152, v153
	flat_store_dwordx4 v[168:169], v[146:149] offset:256
	ds_read_b64 v[150:151], v1
	s_waitcnt lgkmcnt(0)
; __device__ __forceinline__ unsigned cvt_pk_bf16(float lo, float hi) { unsigned r; asm volatile("v_cvt_pk_bf16_f32 %0, %1, %2" : "=v"(r) : "v"(lo), "v"(hi)); return r; }
; #define PG8_BAR __builtin_amdgcn_s_barrier()
;     __device__ __forceinline__ void operator()(f32x4 (&acc)[2][2][4][2], const Unit& u, int wr, int wc, int fr, int fq, PG8_LAS float* sl) const {
;     ...
;                 for (int m = 0; m < 4; ++m) {
;                     const int lr = lr0 + ai * HALF + m * 16; const float mu = sl[2 * lr], rstd = sl[2 * lr + 1];
;                     const size_t off = (size_t)(u.pm * BM + lr) * 1024 + col;
;                     const f32x4 y0 = (acc[ai][bj][m][0] - mu) * rstd * g0 + b0, y1 = (acc[ai][bj][m][1] - mu) * rstd * g1 + b1;
;                     *(f32x4*)(Xout + off) = y0; *(f32x4*)(Xout + off + 4) = y1;
;                     u32x4 w; w.x = cvt_pk_bf16(y0[0], y0[1]); w.y = cvt_pk_bf16(y0[2], y0[3]); w.z = cvt_pk_bf16(y1[0], y1[1]); w.w = cvt_pk_bf16(y1[2], y1[3]);
;                     *(u32x4*)(XB + off) = w;
;                     __builtin_amdgcn_sched_barrier(0);
;                 }
; template <class Epi, class Sched>
; __device__ __forceinline__ void gemm_phase(PG8_LAS unsigned char* lds, const Gemm g, const Sched& S, const Epi& E) {
;     ...
;         if (!has_next) break;
;         if (!S.carry(ui))
; #pragma unroll
;         for (int a = 0; a < 2; ++a)
; #pragma unroll
;             for (int b = 0; b < 2; ++b)
; #pragma unroll
;                 for (int m = 0; m < 4; ++m)
; #pragma unroll
;                     for (int n = 0; n < 2; ++n) acc[a][b][m][n] = (f32x4){0.f, 0.f, 0.f, 0.f};
;         cur = nxt; cA = nA; cB = nB; ++ui;
;         if (wr == 1) PG8_BAR;
	v_sub_f32_e32 v147, v33, v150
	v_sub_f32_e32 v146, v32, v150
	v_sub_f32_e32 v149, v31, v150
	v_sub_f32_e32 v148, v30, v150
	v_pk_mul_f32 v[152:153], v[150:151], v[148:149] op_sel:[1,0]
	v_pk_mul_f32 v[146:147], v[150:151], v[146:147] op_sel:[1,0]
	v_sub_f32_e32 v155, v27, v150
	v_pk_fma_f32 v[148:149], v[144:145], v[146:147], v[140:141]
	v_pk_fma_f32 v[146:147], v[142:143], v[152:153], v[138:139]
	v_sub_f32_e32 v153, v29, v150
	v_sub_f32_e32 v152, v28, v150
	v_sub_f32_e32 v154, v26, v150
	v_pk_mul_f32 v[154:155], v[150:151], v[154:155] op_sel:[1,0]
	v_pk_mul_f32 v[150:151], v[150:151], v[152:153] op_sel:[1,0]
	s_nop 0
	v_pk_fma_f32 v[152:153], v[132:133], v[150:151], v[136:137]
	v_pk_fma_f32 v[150:151], v[130:131], v[154:155], v[134:135]
	flat_store_dwordx4 v[162:163], v[146:149] offset:512
	flat_store_dwordx4 v[162:163], v[150:153] offset:528
	s_nop 0
	v_cvt_pk_bf16_f32 v146, v146, v147
	v_cvt_pk_bf16_f32 v147, v148, v149
	v_cvt_pk_bf16_f32 v148, v150, v151
	v_cvt_pk_bf16_f32 v149, v152, v153
	flat_store_dwordx4 v[170:171], v[146:149] offset:256
	ds_read_b64 v[150:151], v196
	s_waitcnt lgkmcnt(0)
	v_sub_f32_e32 v147, v25, v150
	v_sub_f32_e32 v146, v24, v150
	v_sub_f32_e32 v149, v23, v150
	v_sub_f32_e32 v148, v22, v150
	v_pk_mul_f32 v[152:153], v[150:151], v[148:149] op_sel:[1,0]
	v_pk_mul_f32 v[146:147], v[150:151], v[146:147] op_sel:[1,0]
	v_sub_f32_e32 v155, v19, v150
	v_pk_fma_f32 v[148:149], v[144:145], v[146:147], v[140:141]
	v_pk_fma_f32 v[146:147], v[142:143], v[152:153], v[138:139]
	v_sub_f32_e32 v153, v21, v150
	v_sub_f32_e32 v152, v20, v150
	v_sub_f32_e32 v154, v18, v150
	v_pk_mul_f32 v[154:155], v[150:151], v[154:155] op_sel:[1,0]
	v_pk_mul_f32 v[150:151], v[150:151], v[152:153] op_sel:[1,0]
	s_nop 0
	v_pk_fma_f32 v[152:153], v[132:133], v[150:151], v[136:137]
	v_pk_fma_f32 v[150:151], v[130:131], v[154:155], v[134:135]
	flat_store_dwordx4 v[166:167], v[146:149] offset:512
	flat_store_dwordx4 v[166:167], v[150:153] offset:528
	s_nop 0
	v_cvt_pk_bf16_f32 v146, v146, v147
	v_cvt_pk_bf16_f32 v147, v148, v149
	v_cvt_pk_bf16_f32 v148, v150, v151
	v_cvt_pk_bf16_f32 v149, v152, v153
	flat_store_dwordx4 v[174:175], v[146:149] offset:256
	ds_read_b64 v[150:151], v197
	s_waitcnt lgkmcnt(0)
	v_sub_f32_e32 v147, v17, v150
	v_sub_f32_e32 v146, v16, v150
	v_sub_f32_e32 v149, v15, v150
	v_sub_f32_e32 v148, v14, v150
	v_pk_mul_f32 v[152:153], v[150:151], v[148:149] op_sel:[1,0]
	v_pk_mul_f32 v[146:147], v[150:151], v[146:147] op_sel:[1,0]
	v_sub_f32_e32 v155, v11, v150
	v_pk_fma_f32 v[148:149], v[144:145], v[146:147], v[140:141]
	v_pk_fma_f32 v[146:147], v[142:143], v[152:153], v[138:139]
	v_sub_f32_e32 v153, v13, v150
	v_sub_f32_e32 v152, v12, v150
	v_sub_f32_e32 v154, v10, v150
	v_pk_mul_f32 v[154:155], v[150:151], v[154:155] op_sel:[1,0]
	v_pk_mul_f32 v[150:151], v[150:151], v[152:153] op_sel:[1,0]
	s_nop 0
	v_pk_fma_f32 v[152:153], v[132:133], v[150:151], v[136:137]
	v_pk_fma_f32 v[150:151], v[130:131], v[154:155], v[134:135]
	flat_store_dwordx4 v[172:173], v[146:149] offset:512
	flat_store_dwordx4 v[172:173], v[150:153] offset:528
	s_nop 0
	v_cvt_pk_bf16_f32 v146, v146, v147
	v_cvt_pk_bf16_f32 v147, v148, v149
	v_cvt_pk_bf16_f32 v148, v150, v151
	v_cvt_pk_bf16_f32 v149, v152, v153
	flat_store_dwordx4 v[178:179], v[146:149] offset:256
	ds_read_b64 v[146:147], v190
	s_waitcnt lgkmcnt(0)
	v_sub_f32_e32 v149, v9, v146
	v_sub_f32_e32 v148, v8, v146
	v_sub_f32_e32 v151, v7, v146
	v_sub_f32_e32 v150, v6, v146
	v_pk_mul_f32 v[150:151], v[146:147], v[150:151] op_sel:[1,0]
	v_pk_mul_f32 v[148:149], v[146:147], v[148:149] op_sel:[1,0]
	v_pk_fma_f32 v[138:139], v[142:143], v[150:151], v[138:139]
	v_pk_fma_f32 v[140:141], v[144:145], v[148:149], v[140:141]
	v_sub_f32_e32 v143, v5, v146
	v_sub_f32_e32 v142, v4, v146
	v_sub_f32_e32 v145, v3, v146
	v_sub_f32_e32 v144, v2, v146
	v_pk_mul_f32 v[144:145], v[146:147], v[144:145] op_sel:[1,0]
	v_pk_mul_f32 v[142:143], v[146:147], v[142:143] op_sel:[1,0]
	v_pk_fma_f32 v[130:131], v[130:131], v[144:145], v[134:135]
	v_pk_fma_f32 v[132:133], v[132:133], v[142:143], v[136:137]
	flat_store_dwordx4 v[176:177], v[138:141] offset:512
	flat_store_dwordx4 v[176:177], v[130:133] offset:528
	v_cvt_pk_bf16_f32 v134, v138, v139
	v_cvt_pk_bf16_f32 v135, v140, v141
	v_cvt_pk_bf16_f32 v136, v130, v131
	v_cvt_pk_bf16_f32 v137, v132, v133
	flat_store_dwordx4 v[180:181], v[134:137] offset:256
	s_and_b64 vcc, exec, s[40:41]
	s_mov_b64 s[40:41], -1
	s_cbranch_vccnz .LBB0_505
	s_mul_hi_u32 s14, s76, 0xaaaaaaab
	s_lshr_b32 s14, s14, 1
	s_mul_i32 s14, s14, 3
	s_sub_i32 s14, s76, s14
	s_cmp_lg_u32 s14, 2
	v_readlane_b32 s18, v255, 13
	s_cselect_b64 s[14:15], -1, 0
	v_readlane_b32 s19, v255, 14
	s_and_b64 s[14:15], s[18:19], s[14:15]
	s_and_b64 vcc, exec, s[14:15]
	s_cbranch_vccnz .LBB0_557
.LBB0_557:
	s_andn2_b64 vcc, exec, s[16:17]
	s_cbranch_vccnz .LBB0_504
	s_barrier
	s_branch .LBB0_504
